# thin 32-column dkv GEMM: redundant (clamped) B-row LDS-DMA loads removed (3 of 4 B loads per wave per k-stage)
# speedup vs baseline: 1.0251x; 1.0010x over previous
; template <bool SWAP, class Epi, bool THIN = false> ...
;     ...
;     if (w < full * 8 * NT) { const int sr = w / (8 * NT), rem = w - sr * 8 * NT; nt = rem >> 3; mt = sr * 8 + (rem & 7); }
;     else { const int w2 = w - full * 8 * NT, rl = MT - full * 8; nt = w2 / rl; mt = full * 8 + (w2 - nt * rl); }
;     unsigned ap[4], bp[4];
; #pragma unroll
;     for (int i = 0; i < 4; ++i) {
;       const int r = (tid >> 3) + 64 * i;
;       const int cs = tid & 7;
;       const int c = ((cs ^ ((r >> 1) & 7)) << 3);
;       const int sub = 2 * mt + (r >> 7);
;       const int g = sub / tpg, ti = sub - g * tpg;
;       int rig = ti * step - halo + (r & 127); rig = rig < 0 ? 0 : (rig > grows - 1 ? grows - 1 : rig);
;       ap[i] = (unsigned)((g * a_gstride + a_goff + rig) * lda + c);
;       int br = nt * 256 + r; br = br > N - 1 ? N - 1 : br;
;       bp[i] = (unsigned)(br * K + c);
;     }
;     const bool have_next = false;
;     f32x4 acc[4][8];
; #pragma unroll
;     for (int m = 0; m < 4; ++m)
; #pragma unroll
;       for (int n = 0; n < 8; ++n) acc[m][n] = (f32x4){0.f, 0.f, 0.f, 0.f};
;     if (!pre_issued) {
; #pragma unroll
;       for (int i = 0; i < 4; ++i) { GLDS16(A + (size_t)ap[i], smem + tid * 16 + i * 8192); GLDS16(Bt + (size_t)bp[i], smem + 32768 + tid * 16 + i * 8192); }
;     }
;     pre_issued = have_next;
;     for (int st = 0; st < ns; ++st) {
;       asm volatile("s_waitcnt vmcnt(0)" ::: "memory");
;       __builtin_amdgcn_s_barrier();
;       asm volatile("" ::: "memory");
;       if (st + 1 < ns) {
;         char* nb = smem + ((st + 1) & 1) * 65536;
;         const int ko = (st + 1) * 64;
; #pragma unroll
;         for (int i = 0; i < 4; ++i) { GLDS16(A + (size_t)(ap[i] + ko), nb + tid * 16 + i * 8192); GLDS16(Bt + (size_t)(bp[i] + ko), nb + 32768 + tid * 16 + i * 8192); }
;       }
;       const char* sa = smem + (st & 1) * 65536 + (wr * 64 + fr) * 128;
;       const char* sb = smem + (st & 1) * 65536 + 32768 + (wc * 128 + fr) * 128;
;       if constexpr (THIN) {
;         if (wc == 0) {
; #pragma unroll
;           for (int ks = 0; ks < 2; ++ks) {
;             bf16x8 af[4], bf[2];
; #pragma unroll
;             for (int m = 0; m < 4; ++m) af[m] = *(const bf16x8*)(sa + m * 2048 + (((ks * 4 + fq) ^ swz) << 4));
; #pragma unroll
;             for (int n = 0; n < 2; ++n) bf[n] = *(const bf16x8*)(sb + n * 2048 + (((ks * 4 + fq) ^ swz) << 4));
.LBB0_1525:
	s_ashr_i32 s7, s3, 31
	s_lshr_b32 s7, s7, 29
	s_add_i32 s6, s3, 0x108
	s_add_i32 s7, s3, s7
	s_and_b32 s7, s7, -8
	s_and_b32 s6, s6, 7
	s_or_b32 s6, s7, s6
	s_lshl_b32 s9, s6, 1
	v_add_u32_e32 v2, s9, v57
	v_mul_hi_i32 v4, v2, s33
	v_lshrrev_b32_e32 v5, 31, v4
	v_ashrrev_i32_e32 v4, 2, v4
	v_add_u32_e32 v6, v4, v5
	s_sub_i32 s8, s3, s7
	v_mad_u64_u32 v[4:5], s[6:7], v6, s74, v[2:3]
	v_lshl_or_b32 v2, v4, 7, v58
	v_min_i32_e32 v2, 0x8ff, v2
	v_cmp_lt_i32_e32 vcc, -1, v4
	s_ashr_i32 s46, s8, 3
	s_lshl_b32 s8, s46, 8
	v_cndmask_b32_e32 v2, 0, v2, vcc
	v_mad_u64_u32 v[4:5], s[6:7], v6, s75, v[2:3]
	v_lshl_or_b32 v2, v4, 10, v55
	v_add_u32_e32 v4, s8, v54
	v_min_i32_e32 v4, 31, v4
	v_lshl_or_b32 v38, v4, 10, v55
	v_add_u32_e32 v4, s9, v60
	v_mul_hi_i32 v5, v4, s33
	v_lshrrev_b32_e32 v6, 31, v5
	v_ashrrev_i32_e32 v5, 2, v5
	v_add_u32_e32 v6, v5, v6
	v_mad_u64_u32 v[4:5], s[6:7], v6, s74, v[4:5]
	v_lshl_or_b32 v5, v4, 7, v61
	v_min_i32_e32 v5, 0x8ff, v5
	v_cmp_lt_i32_e32 vcc, -1, v4
	v_add_u32_e32 v8, s9, v65
	v_lshl_add_u64 v[46:47], v[2:3], 1, s[36:37]
	v_cndmask_b32_e32 v4, 0, v5, vcc
	v_mad_u64_u32 v[4:5], s[6:7], v6, s75, v[4:5]
	v_add_u32_e32 v5, s8, v59
	v_min_i32_e32 v5, 31, v5
	v_add_u32_e32 v6, s9, v63
	v_lshl_or_b32 v40, v5, 10, v55
	v_mul_hi_i32 v5, v6, s33
	v_lshrrev_b32_e32 v7, 31, v5
	v_ashrrev_i32_e32 v5, 2, v5
	v_add_u32_e32 v5, v5, v7
	v_mad_u64_u32 v[6:7], s[6:7], v5, s74, v[6:7]
	v_lshl_or_b32 v7, v6, 7, v58
	v_min_i32_e32 v7, 0x8ff, v7
	v_cmp_lt_i32_e32 vcc, -1, v6
	v_mov_b32_e32 v39, v3
	v_lshl_or_b32 v4, v4, 10, v55
	v_cndmask_b32_e32 v6, 0, v7, vcc
	v_mad_u64_u32 v[6:7], s[6:7], v5, s75, v[6:7]
	v_add_u32_e32 v5, s8, v62
	v_min_i32_e32 v5, 31, v5
	v_lshl_or_b32 v42, v5, 10, v55
	v_mul_hi_i32 v5, v8, s33
	v_lshrrev_b32_e32 v7, 31, v5
	v_ashrrev_i32_e32 v5, 2, v5
	v_add_u32_e32 v5, v5, v7
	v_mad_u64_u32 v[8:9], s[6:7], v5, s74, v[8:9]
	v_lshl_or_b32 v7, v8, 7, v66
	v_min_i32_e32 v7, 0x8ff, v7
	v_cmp_lt_i32_e32 vcc, -1, v8
	v_lshl_add_u64 v[10:11], v[38:39], 1, s[18:19]
	v_mov_b32_e32 v41, v3
	v_cndmask_b32_e32 v8, 0, v7, vcc
	v_mad_u64_u32 v[8:9], s[6:7], v5, s75, v[8:9]
	v_add_u32_e32 v5, s8, v64
	v_readfirstlane_b32 s6, v56
	v_min_i32_e32 v5, 31, v5
	s_mov_b32 m0, s6
	v_readfirstlane_b32 s6, v67
	v_lshl_or_b32 v44, v5, 10, v55
	global_load_lds_dwordx4 v[46:47], off
	s_mov_b32 m0, s6
	v_mov_b32_e32 v5, v3
	v_readfirstlane_b32 s6, v68
	global_load_lds_dwordx4 v[10:11], off
	v_lshl_add_u64 v[48:49], v[4:5], 1, s[36:37]
	s_mov_b32 m0, s6
	v_readfirstlane_b32 s6, v69
	v_lshl_or_b32 v6, v6, 10, v55
	global_load_lds_dwordx4 v[48:49], off
	v_lshl_add_u64 v[4:5], v[40:41], 1, s[18:19]
	s_mov_b32 m0, s6
	v_mov_b32_e32 v7, v3
	v_readfirstlane_b32 s6, v70
	v_lshl_add_u64 v[50:51], v[6:7], 1, s[36:37]
	s_mov_b32 m0, s6
	v_mov_b32_e32 v43, v3
	v_readfirstlane_b32 s6, v71
	v_lshl_or_b32 v8, v8, 10, v55
	global_load_lds_dwordx4 v[50:51], off
	v_lshl_add_u64 v[4:5], v[42:43], 1, s[18:19]
	s_mov_b32 m0, s6
	v_mov_b32_e32 v9, v3
	v_readfirstlane_b32 s6, v72
	v_lshl_add_u64 v[52:53], v[8:9], 1, s[36:37]
	s_mov_b32 m0, s6
	v_mov_b32_e32 v45, v3
	v_readfirstlane_b32 s6, v73
	global_load_lds_dwordx4 v[52:53], off
	v_lshl_add_u64 v[4:5], v[44:45], 1, s[18:19]
	s_mov_b32 m0, s6
	v_readfirstlane_b32 s6, v74
	s_waitcnt vmcnt(0)
	s_barrier
	v_lshl_add_u64 v[4:5], v[46:47], 0, s[22:23]
	s_mov_b32 m0, s6
	v_or_b32_e32 v2, 64, v38
	v_readfirstlane_b32 s6, v75
	global_load_lds_dwordx4 v[4:5], off
	v_lshl_add_u64 v[4:5], v[2:3], 1, s[18:19]
	s_mov_b32 m0, s6
	v_readfirstlane_b32 s6, v76
	global_load_lds_dwordx4 v[4:5], off
	v_lshl_add_u64 v[4:5], v[48:49], 0, s[22:23]
	s_mov_b32 m0, s6
	v_or_b32_e32 v2, 64, v40
	v_readfirstlane_b32 s6, v77
	global_load_lds_dwordx4 v[4:5], off
	v_lshl_add_u64 v[4:5], v[2:3], 1, s[18:19]
	s_mov_b32 m0, s6
	v_readfirstlane_b32 s6, v78
	v_lshl_add_u64 v[4:5], v[50:51], 0, s[22:23]
	s_mov_b32 m0, s6
	v_or_b32_e32 v2, 64, v42
	v_readfirstlane_b32 s6, v79
	global_load_lds_dwordx4 v[4:5], off
	v_lshl_add_u64 v[4:5], v[2:3], 1, s[18:19]
	s_mov_b32 m0, s6
	v_readfirstlane_b32 s6, v80
	v_lshl_add_u64 v[4:5], v[52:53], 0, s[22:23]
	s_mov_b32 m0, s6
	v_or_b32_e32 v2, 64, v44
	v_readfirstlane_b32 s6, v81
	global_load_lds_dwordx4 v[4:5], off
	v_lshl_add_u64 v[4:5], v[2:3], 1, s[18:19]
	s_mov_b32 m0, s6
	v_mov_b32_e32 v2, v3
	v_mov_b32_e32 v4, v3
	v_mov_b32_e32 v5, v3
	v_mov_b64_e32 v[28:29], v[4:5]
	v_mov_b64_e32 v[24:25], v[4:5]
	v_mov_b64_e32 v[20:21], v[4:5]
	v_mov_b64_e32 v[16:17], v[4:5]
	v_mov_b64_e32 v[12:13], v[4:5]
	v_mov_b64_e32 v[8:9], v[4:5]
	v_mov_b64_e32 v[32:33], v[4:5]
	v_mov_b64_e32 v[36:37], v[4:5]
	v_mov_b64_e32 v[26:27], v[2:3]
	v_mov_b64_e32 v[22:23], v[2:3]
	v_mov_b64_e32 v[18:19], v[2:3]
	v_mov_b64_e32 v[14:15], v[2:3]
	v_mov_b64_e32 v[10:11], v[2:3]
	v_mov_b64_e32 v[6:7], v[2:3]
	v_mov_b64_e32 v[30:31], v[2:3]
	v_mov_b64_e32 v[34:35], v[2:3]
	s_and_saveexec_b64 s[6:7], s[4:5]
	s_cbranch_execz .LBB0_1527
	ds_read_b128 v[4:7], v83 offset:32768
	ds_read_b128 v[8:11], v83 offset:34816
	ds_read_b128 v[12:15], v82
	ds_read_b128 v[16:19], v82 offset:2048
	ds_read_b128 v[28:31], v82 offset:4096
	ds_read_b128 v[32:35], v82 offset:6144
	ds_read_b128 v[102:105], v85 offset:32768
	s_waitcnt lgkmcnt(0)
	v_mfma_f32_16x16x32_bf16 v[20:23], v[4:7], v[12:15], 0
	v_mfma_f32_16x16x32_bf16 v[12:15], v[8:11], v[12:15], 0
	v_mfma_f32_16x16x32_bf16 v[24:27], v[4:7], v[16:19], 0
	v_mfma_f32_16x16x32_bf16 v[16:19], v[8:11], v[16:19], 0
	v_mfma_f32_16x16x32_bf16 v[98:101], v[8:11], v[28:31], 0
	v_mfma_f32_16x16x32_bf16 v[106:109], v[8:11], v[32:35], 0
	ds_read_b128 v[110:113], v85 offset:34816
	ds_read_b128 v[8:11], v84
	ds_read_b128 v[114:117], v84 offset:2048
	v_mfma_f32_16x16x32_bf16 v[94:97], v[4:7], v[28:31], 0
	v_mfma_f32_16x16x32_bf16 v[4:7], v[4:7], v[32:35], 0
	s_waitcnt lgkmcnt(0)
	v_mfma_f32_16x16x32_bf16 v[34:37], v[102:105], v[8:11], v[20:23]
	v_mfma_f32_16x16x32_bf16 v[30:33], v[110:113], v[8:11], v[12:15]
	v_mfma_f32_16x16x32_bf16 v[26:29], v[102:105], v[114:117], v[24:27]
	v_mfma_f32_16x16x32_bf16 v[22:25], v[110:113], v[114:117], v[16:19]
	ds_read_b128 v[8:11], v84 offset:4096
	ds_read_b128 v[114:117], v84 offset:6144
	s_waitcnt lgkmcnt(0)
	v_mfma_f32_16x16x32_bf16 v[18:21], v[102:105], v[8:11], v[94:97]
	v_mfma_f32_16x16x32_bf16 v[14:17], v[110:113], v[8:11], v[98:101]
	v_mfma_f32_16x16x32_bf16 v[10:13], v[102:105], v[114:117], v[4:7]
	v_mfma_f32_16x16x32_bf16 v[6:9], v[110:113], v[114:117], v[106:109]
; #define GLDS16(gp, lp) __builtin_amdgcn_global_load_lds((const unsigned*)(gp), (__attribute__((address_space(3))) unsigned*)(lp), 16, 0, 0)
; template <bool SWAP, class Epi, bool THIN = false> ...
;     ...
;     for (int st = 0; st < ns; ++st) {
;       asm volatile("s_waitcnt vmcnt(0)" ::: "memory");
;       __builtin_amdgcn_s_barrier();
;       asm volatile("" ::: "memory");
;       if (st + 1 < ns) {
;         char* nb = smem + ((st + 1) & 1) * 65536;
;         const int ko = (st + 1) * 64;
; #pragma unroll
;         for (int i = 0; i < 4; ++i) { GLDS16(A + (size_t)(ap[i] + ko), nb + tid * 16 + i * 8192); GLDS16(Bt + (size_t)(bp[i] + ko), nb + 32768 + tid * 16 + i * 8192); }
;       }
;       const char* sa = smem + (st & 1) * 65536 + (wr * 64 + fr) * 128;
;       const char* sb = smem + (st & 1) * 65536 + 32768 + (wc * 128 + fr) * 128;
;       if constexpr (THIN) {
;         if (wc == 0) {
; #pragma unroll
;           for (int ks = 0; ks < 2; ++ks) {
;             bf16x8 af[4], bf[2];
; #pragma unroll
;             for (int m = 0; m < 4; ++m) af[m] = *(const bf16x8*)(sa + m * 2048 + (((ks * 4 + fq) ^ swz) << 4));
; #pragma unroll
;             for (int n = 0; n < 2; ++n) bf[n] = *(const bf16x8*)(sb + n * 2048 + (((ks * 4 + fq) ^ swz) << 4));
; #pragma unroll
;             for (int m = 0; m < 4; ++m)
; #pragma unroll
;               for (int n = 0; n < 2; ++n)
;                 acc[m][n] = SWAP ? __builtin_amdgcn_mfma_f32_16x16x32_bf16(bf[n], af[m], acc[m][n], 0, 0, 0)
;                                  : __builtin_amdgcn_mfma_f32_16x16x32_bf16(af[m], bf[n], acc[m][n], 0, 0, 0);
;           }
.LBB0_1527:
	s_or_b64 exec, exec, s[6:7]
	v_readfirstlane_b32 s6, v56
	s_waitcnt vmcnt(0)
	s_barrier
	v_lshl_add_u64 v[4:5], v[46:47], 0, s[24:25]
	s_mov_b32 m0, s6
	v_or_b32_e32 v2, 0x80, v38
	v_readfirstlane_b32 s6, v67
	global_load_lds_dwordx4 v[4:5], off
	v_lshl_add_u64 v[4:5], v[2:3], 1, s[18:19]
	s_mov_b32 m0, s6
	v_readfirstlane_b32 s6, v68
	global_load_lds_dwordx4 v[4:5], off
	v_lshl_add_u64 v[4:5], v[48:49], 0, s[24:25]
	s_mov_b32 m0, s6
	v_or_b32_e32 v2, 0x80, v40
	v_readfirstlane_b32 s6, v69
	global_load_lds_dwordx4 v[4:5], off
	v_lshl_add_u64 v[4:5], v[2:3], 1, s[18:19]
	s_mov_b32 m0, s6
	v_readfirstlane_b32 s6, v70
	v_lshl_add_u64 v[4:5], v[50:51], 0, s[24:25]
	s_mov_b32 m0, s6
	v_or_b32_e32 v2, 0x80, v42
	v_readfirstlane_b32 s6, v71
	global_load_lds_dwordx4 v[4:5], off
	v_lshl_add_u64 v[4:5], v[2:3], 1, s[18:19]
	s_mov_b32 m0, s6
	v_readfirstlane_b32 s6, v72
	v_lshl_add_u64 v[4:5], v[52:53], 0, s[24:25]
	s_mov_b32 m0, s6
	v_or_b32_e32 v2, 0x80, v44
	v_readfirstlane_b32 s6, v73
	global_load_lds_dwordx4 v[4:5], off
	v_lshl_add_u64 v[4:5], v[2:3], 1, s[18:19]
	s_mov_b32 m0, s6
	s_nop 0
	s_and_saveexec_b64 s[6:7], s[4:5]
	s_cbranch_execz .LBB0_1529
	ds_read_b128 v[94:97], v87
	ds_read_b128 v[98:101], v87 offset:2048
	ds_read_b128 v[102:105], v86
	ds_read_b128 v[106:109], v86 offset:2048
	s_waitcnt lgkmcnt(0)
	v_mfma_f32_16x16x32_bf16 v[34:37], v[94:97], v[102:105], v[34:37]
	v_mfma_f32_16x16x32_bf16 v[30:33], v[98:101], v[102:105], v[30:33]
	v_mfma_f32_16x16x32_bf16 v[26:29], v[94:97], v[106:109], v[26:29]
	v_mfma_f32_16x16x32_bf16 v[22:25], v[98:101], v[106:109], v[22:25]
	ds_read_b128 v[102:105], v86 offset:4096
	ds_read_b128 v[106:109], v86 offset:6144
	s_waitcnt lgkmcnt(0)
	v_mfma_f32_16x16x32_bf16 v[18:21], v[94:97], v[102:105], v[18:21]
	v_mfma_f32_16x16x32_bf16 v[10:13], v[94:97], v[106:109], v[10:13]
	ds_read_b128 v[94:97], v89
	v_mfma_f32_16x16x32_bf16 v[14:17], v[98:101], v[102:105], v[14:17]
	v_mfma_f32_16x16x32_bf16 v[4:7], v[98:101], v[106:109], v[6:9]
	ds_read_b128 v[98:101], v89 offset:2048
	ds_read_b128 v[102:105], v88
	ds_read_b128 v[106:109], v88 offset:2048
	s_waitcnt lgkmcnt(0)
	v_mfma_f32_16x16x32_bf16 v[34:37], v[94:97], v[102:105], v[34:37]
	v_mfma_f32_16x16x32_bf16 v[30:33], v[98:101], v[102:105], v[30:33]
	v_mfma_f32_16x16x32_bf16 v[26:29], v[94:97], v[106:109], v[26:29]
	v_mfma_f32_16x16x32_bf16 v[22:25], v[98:101], v[106:109], v[22:25]
	ds_read_b128 v[102:105], v88 offset:4096
	ds_read_b128 v[106:109], v88 offset:6144
	s_waitcnt lgkmcnt(0)
	v_mfma_f32_16x16x32_bf16 v[18:21], v[94:97], v[102:105], v[18:21]
	v_mfma_f32_16x16x32_bf16 v[14:17], v[98:101], v[102:105], v[14:17]
	v_mfma_f32_16x16x32_bf16 v[10:13], v[94:97], v[106:109], v[10:13]
	v_mfma_f32_16x16x32_bf16 v[6:9], v[98:101], v[106:109], v[4:7]
.LBB0_1529:
	s_or_b64 exec, exec, s[6:7]
	v_readfirstlane_b32 s6, v74
	s_waitcnt vmcnt(0)
	s_barrier
	v_lshl_add_u64 v[4:5], v[46:47], 0, s[26:27]
	s_mov_b32 m0, s6
	v_or_b32_e32 v2, 0xc0, v38
	v_readfirstlane_b32 s6, v75
	global_load_lds_dwordx4 v[4:5], off
	v_lshl_add_u64 v[4:5], v[2:3], 1, s[18:19]
	s_mov_b32 m0, s6
	v_readfirstlane_b32 s6, v76
	global_load_lds_dwordx4 v[4:5], off
	v_lshl_add_u64 v[4:5], v[48:49], 0, s[26:27]
	s_mov_b32 m0, s6
	v_or_b32_e32 v2, 0xc0, v40
	v_readfirstlane_b32 s6, v77
	global_load_lds_dwordx4 v[4:5], off
	v_lshl_add_u64 v[4:5], v[2:3], 1, s[18:19]
	s_mov_b32 m0, s6
	v_readfirstlane_b32 s6, v78
	v_lshl_add_u64 v[4:5], v[50:51], 0, s[26:27]
	s_mov_b32 m0, s6
	v_or_b32_e32 v2, 0xc0, v42
	v_readfirstlane_b32 s6, v79
	global_load_lds_dwordx4 v[4:5], off
	v_lshl_add_u64 v[4:5], v[2:3], 1, s[18:19]
	s_mov_b32 m0, s6
	v_readfirstlane_b32 s6, v80
	v_lshl_add_u64 v[4:5], v[52:53], 0, s[26:27]
	s_mov_b32 m0, s6
	v_or_b32_e32 v2, 0xc0, v44
	v_readfirstlane_b32 s6, v81
	global_load_lds_dwordx4 v[4:5], off
	v_lshl_add_u64 v[4:5], v[2:3], 1, s[18:19]
	s_mov_b32 m0, s6
	s_nop 0
	s_and_saveexec_b64 s[6:7], s[4:5]
	s_cbranch_execz .LBB0_1531
	ds_read_b128 v[94:97], v83 offset:32768
	ds_read_b128 v[98:101], v83 offset:34816
	ds_read_b128 v[102:105], v82
	ds_read_b128 v[106:109], v82 offset:2048
	s_waitcnt lgkmcnt(0)
	v_mfma_f32_16x16x32_bf16 v[34:37], v[94:97], v[102:105], v[34:37]
	v_mfma_f32_16x16x32_bf16 v[30:33], v[98:101], v[102:105], v[30:33]
	v_mfma_f32_16x16x32_bf16 v[26:29], v[94:97], v[106:109], v[26:29]
	v_mfma_f32_16x16x32_bf16 v[22:25], v[98:101], v[106:109], v[22:25]
	ds_read_b128 v[102:105], v82 offset:4096
	ds_read_b128 v[106:109], v82 offset:6144
	s_waitcnt lgkmcnt(0)
	v_mfma_f32_16x16x32_bf16 v[18:21], v[94:97], v[102:105], v[18:21]
	v_mfma_f32_16x16x32_bf16 v[10:13], v[94:97], v[106:109], v[10:13]
	ds_read_b128 v[94:97], v85 offset:32768
	v_mfma_f32_16x16x32_bf16 v[14:17], v[98:101], v[102:105], v[14:17]
	v_mfma_f32_16x16x32_bf16 v[4:7], v[98:101], v[106:109], v[6:9]
	ds_read_b128 v[98:101], v85 offset:34816
	ds_read_b128 v[102:105], v84
	ds_read_b128 v[106:109], v84 offset:2048
	s_waitcnt lgkmcnt(0)
	v_mfma_f32_16x16x32_bf16 v[34:37], v[94:97], v[102:105], v[34:37]
	v_mfma_f32_16x16x32_bf16 v[30:33], v[98:101], v[102:105], v[30:33]
	v_mfma_f32_16x16x32_bf16 v[26:29], v[94:97], v[106:109], v[26:29]
	v_mfma_f32_16x16x32_bf16 v[22:25], v[98:101], v[106:109], v[22:25]
	ds_read_b128 v[102:105], v84 offset:4096
	ds_read_b128 v[106:109], v84 offset:6144
	s_waitcnt lgkmcnt(0)
	v_mfma_f32_16x16x32_bf16 v[18:21], v[94:97], v[102:105], v[18:21]
	v_mfma_f32_16x16x32_bf16 v[14:17], v[98:101], v[102:105], v[14:17]
	v_mfma_f32_16x16x32_bf16 v[10:13], v[94:97], v[106:109], v[10:13]
	v_mfma_f32_16x16x32_bf16 v[6:9], v[98:101], v[106:109], v[4:7]
; #define GLDS16(gp, lp) __builtin_amdgcn_global_load_lds((const unsigned*)(gp), (__attribute__((address_space(3))) unsigned*)(lp), 16, 0, 0)
; template <bool SWAP, class Epi, bool THIN = false> ...
;     ...
;     for (int st = 0; st < ns; ++st) {
;       asm volatile("s_waitcnt vmcnt(0)" ::: "memory");
;       __builtin_amdgcn_s_barrier();
;       asm volatile("" ::: "memory");
;       if (st + 1 < ns) {
;         char* nb = smem + ((st + 1) & 1) * 65536;
;         const int ko = (st + 1) * 64;
; #pragma unroll
;         for (int i = 0; i < 4; ++i) { GLDS16(A + (size_t)(ap[i] + ko), nb + tid * 16 + i * 8192); GLDS16(Bt + (size_t)(bp[i] + ko), nb + 32768 + tid * 16 + i * 8192); }
;       }
;       const char* sa = smem + (st & 1) * 65536 + (wr * 64 + fr) * 128;
;       const char* sb = smem + (st & 1) * 65536 + 32768 + (wc * 128 + fr) * 128;
;       if constexpr (THIN) {
;         if (wc == 0) {
; #pragma unroll
;           for (int ks = 0; ks < 2; ++ks) {
;             bf16x8 af[4], bf[2];
; #pragma unroll
;             for (int m = 0; m < 4; ++m) af[m] = *(const bf16x8*)(sa + m * 2048 + (((ks * 4 + fq) ^ swz) << 4));
; #pragma unroll
;             for (int n = 0; n < 2; ++n) bf[n] = *(const bf16x8*)(sb + n * 2048 + (((ks * 4 + fq) ^ swz) << 4));
; #pragma unroll
;             for (int m = 0; m < 4; ++m)
; #pragma unroll
;               for (int n = 0; n < 2; ++n)
;                 acc[m][n] = SWAP ? __builtin_amdgcn_mfma_f32_16x16x32_bf16(bf[n], af[m], acc[m][n], 0, 0, 0)
;                                  : __builtin_amdgcn_mfma_f32_16x16x32_bf16(af[m], bf[n], acc[m][n], 0, 0, 0);
;           }
.LBB0_1531:
	s_or_b64 exec, exec, s[6:7]
	v_readfirstlane_b32 s6, v56
	s_waitcnt vmcnt(0)
	s_barrier
	v_lshl_add_u64 v[4:5], v[46:47], 0, s[28:29]
	s_mov_b32 m0, s6
	v_or_b32_e32 v2, 0x100, v38
	v_readfirstlane_b32 s6, v67
	global_load_lds_dwordx4 v[4:5], off
	v_lshl_add_u64 v[4:5], v[2:3], 1, s[18:19]
	s_mov_b32 m0, s6
	v_readfirstlane_b32 s6, v68
	global_load_lds_dwordx4 v[4:5], off
	v_lshl_add_u64 v[4:5], v[48:49], 0, s[28:29]
	s_mov_b32 m0, s6
	v_or_b32_e32 v2, 0x100, v40
	v_readfirstlane_b32 s6, v69
	global_load_lds_dwordx4 v[4:5], off
	v_lshl_add_u64 v[4:5], v[2:3], 1, s[18:19]
	s_mov_b32 m0, s6
	v_readfirstlane_b32 s6, v70
	v_lshl_add_u64 v[4:5], v[50:51], 0, s[28:29]
	s_mov_b32 m0, s6
	v_or_b32_e32 v2, 0x100, v42
	v_readfirstlane_b32 s6, v71
	global_load_lds_dwordx4 v[4:5], off
	v_lshl_add_u64 v[4:5], v[2:3], 1, s[18:19]
	s_mov_b32 m0, s6
	v_readfirstlane_b32 s6, v72
	v_lshl_add_u64 v[4:5], v[52:53], 0, s[28:29]
	s_mov_b32 m0, s6
	v_or_b32_e32 v2, 0x100, v44
	v_readfirstlane_b32 s6, v73
	global_load_lds_dwordx4 v[4:5], off
	v_lshl_add_u64 v[4:5], v[2:3], 1, s[18:19]
	s_mov_b32 m0, s6
	s_nop 0
	s_and_saveexec_b64 s[6:7], s[4:5]
	s_cbranch_execz .LBB0_1533
	ds_read_b128 v[94:97], v87
	ds_read_b128 v[98:101], v87 offset:2048
	ds_read_b128 v[102:105], v86
	ds_read_b128 v[106:109], v86 offset:2048
	s_waitcnt lgkmcnt(0)
	v_mfma_f32_16x16x32_bf16 v[34:37], v[94:97], v[102:105], v[34:37]
	v_mfma_f32_16x16x32_bf16 v[30:33], v[98:101], v[102:105], v[30:33]
	v_mfma_f32_16x16x32_bf16 v[26:29], v[94:97], v[106:109], v[26:29]
	v_mfma_f32_16x16x32_bf16 v[22:25], v[98:101], v[106:109], v[22:25]
	ds_read_b128 v[102:105], v86 offset:4096
	ds_read_b128 v[106:109], v86 offset:6144
	s_waitcnt lgkmcnt(0)
	v_mfma_f32_16x16x32_bf16 v[18:21], v[94:97], v[102:105], v[18:21]
	v_mfma_f32_16x16x32_bf16 v[10:13], v[94:97], v[106:109], v[10:13]
	ds_read_b128 v[94:97], v89
	v_mfma_f32_16x16x32_bf16 v[14:17], v[98:101], v[102:105], v[14:17]
	v_mfma_f32_16x16x32_bf16 v[4:7], v[98:101], v[106:109], v[6:9]
	ds_read_b128 v[98:101], v89 offset:2048
	ds_read_b128 v[102:105], v88
	ds_read_b128 v[106:109], v88 offset:2048
	s_waitcnt lgkmcnt(0)
	v_mfma_f32_16x16x32_bf16 v[34:37], v[94:97], v[102:105], v[34:37]
	v_mfma_f32_16x16x32_bf16 v[30:33], v[98:101], v[102:105], v[30:33]
	v_mfma_f32_16x16x32_bf16 v[26:29], v[94:97], v[106:109], v[26:29]
	v_mfma_f32_16x16x32_bf16 v[22:25], v[98:101], v[106:109], v[22:25]
	ds_read_b128 v[102:105], v88 offset:4096
	ds_read_b128 v[106:109], v88 offset:6144
	s_waitcnt lgkmcnt(0)
	v_mfma_f32_16x16x32_bf16 v[18:21], v[94:97], v[102:105], v[18:21]
	v_mfma_f32_16x16x32_bf16 v[14:17], v[98:101], v[102:105], v[14:17]
	v_mfma_f32_16x16x32_bf16 v[10:13], v[94:97], v[106:109], v[10:13]
	v_mfma_f32_16x16x32_bf16 v[6:9], v[98:101], v[106:109], v[4:7]
.LBB0_1533:
	s_or_b64 exec, exec, s[6:7]
	v_readfirstlane_b32 s6, v74
	s_waitcnt vmcnt(0)
	s_barrier
	v_lshl_add_u64 v[4:5], v[46:47], 0, s[38:39]
	s_mov_b32 m0, s6
	v_or_b32_e32 v2, 0x140, v38
	v_readfirstlane_b32 s6, v75
	global_load_lds_dwordx4 v[4:5], off
	v_lshl_add_u64 v[4:5], v[2:3], 1, s[18:19]
	s_mov_b32 m0, s6
	v_readfirstlane_b32 s6, v76
	global_load_lds_dwordx4 v[4:5], off
	v_lshl_add_u64 v[4:5], v[48:49], 0, s[38:39]
	s_mov_b32 m0, s6
	v_or_b32_e32 v2, 0x140, v40
	v_readfirstlane_b32 s6, v77
	global_load_lds_dwordx4 v[4:5], off
	v_lshl_add_u64 v[4:5], v[2:3], 1, s[18:19]
	s_mov_b32 m0, s6
	v_readfirstlane_b32 s6, v78
	v_lshl_add_u64 v[4:5], v[50:51], 0, s[38:39]
	s_mov_b32 m0, s6
	v_or_b32_e32 v2, 0x140, v42
	v_readfirstlane_b32 s6, v79
	global_load_lds_dwordx4 v[4:5], off
	v_lshl_add_u64 v[4:5], v[2:3], 1, s[18:19]
	s_mov_b32 m0, s6
	v_readfirstlane_b32 s6, v80
	v_lshl_add_u64 v[4:5], v[52:53], 0, s[38:39]
	s_mov_b32 m0, s6
	v_or_b32_e32 v2, 0x140, v44
	v_readfirstlane_b32 s6, v81
	global_load_lds_dwordx4 v[4:5], off
	v_lshl_add_u64 v[4:5], v[2:3], 1, s[18:19]
	s_mov_b32 m0, s6
	s_nop 0
	s_and_saveexec_b64 s[6:7], s[4:5]
	s_cbranch_execz .LBB0_1535
	ds_read_b128 v[94:97], v83 offset:32768
	ds_read_b128 v[98:101], v83 offset:34816
	ds_read_b128 v[102:105], v82
	ds_read_b128 v[106:109], v82 offset:2048
	s_waitcnt lgkmcnt(0)
	v_mfma_f32_16x16x32_bf16 v[34:37], v[94:97], v[102:105], v[34:37]
	v_mfma_f32_16x16x32_bf16 v[30:33], v[98:101], v[102:105], v[30:33]
	v_mfma_f32_16x16x32_bf16 v[26:29], v[94:97], v[106:109], v[26:29]
	v_mfma_f32_16x16x32_bf16 v[22:25], v[98:101], v[106:109], v[22:25]
	ds_read_b128 v[102:105], v82 offset:4096
	ds_read_b128 v[106:109], v82 offset:6144
	s_waitcnt lgkmcnt(0)
	v_mfma_f32_16x16x32_bf16 v[18:21], v[94:97], v[102:105], v[18:21]
	v_mfma_f32_16x16x32_bf16 v[10:13], v[94:97], v[106:109], v[10:13]
	ds_read_b128 v[94:97], v85 offset:32768
	v_mfma_f32_16x16x32_bf16 v[14:17], v[98:101], v[102:105], v[14:17]
	v_mfma_f32_16x16x32_bf16 v[4:7], v[98:101], v[106:109], v[6:9]
	ds_read_b128 v[98:101], v85 offset:34816
	ds_read_b128 v[102:105], v84
	ds_read_b128 v[106:109], v84 offset:2048
	s_waitcnt lgkmcnt(0)
	v_mfma_f32_16x16x32_bf16 v[34:37], v[94:97], v[102:105], v[34:37]
	v_mfma_f32_16x16x32_bf16 v[30:33], v[98:101], v[102:105], v[30:33]
	v_mfma_f32_16x16x32_bf16 v[26:29], v[94:97], v[106:109], v[26:29]
	v_mfma_f32_16x16x32_bf16 v[22:25], v[98:101], v[106:109], v[22:25]
	ds_read_b128 v[102:105], v84 offset:4096
	ds_read_b128 v[106:109], v84 offset:6144
	s_waitcnt lgkmcnt(0)
	v_mfma_f32_16x16x32_bf16 v[18:21], v[94:97], v[102:105], v[18:21]
	v_mfma_f32_16x16x32_bf16 v[14:17], v[98:101], v[102:105], v[14:17]
	v_mfma_f32_16x16x32_bf16 v[10:13], v[94:97], v[106:109], v[10:13]
	v_mfma_f32_16x16x32_bf16 v[6:9], v[98:101], v[106:109], v[4:7]
; #define GLDS16(gp, lp) __builtin_amdgcn_global_load_lds((const unsigned*)(gp), (__attribute__((address_space(3))) unsigned*)(lp), 16, 0, 0)
; template <bool SWAP, class Epi, bool THIN = false> ...
;     ...
;     for (int st = 0; st < ns; ++st) {
;       asm volatile("s_waitcnt vmcnt(0)" ::: "memory");
;       __builtin_amdgcn_s_barrier();
;       asm volatile("" ::: "memory");
;       if (st + 1 < ns) {
;         char* nb = smem + ((st + 1) & 1) * 65536;
;         const int ko = (st + 1) * 64;
; #pragma unroll
;         for (int i = 0; i < 4; ++i) { GLDS16(A + (size_t)(ap[i] + ko), nb + tid * 16 + i * 8192); GLDS16(Bt + (size_t)(bp[i] + ko), nb + 32768 + tid * 16 + i * 8192); }
;       }
;       const char* sa = smem + (st & 1) * 65536 + (wr * 64 + fr) * 128;
;       const char* sb = smem + (st & 1) * 65536 + 32768 + (wc * 128 + fr) * 128;
;       if constexpr (THIN) {
;         if (wc == 0) {
; #pragma unroll
;           for (int ks = 0; ks < 2; ++ks) {
;             bf16x8 af[4], bf[2];
; #pragma unroll
;             for (int m = 0; m < 4; ++m) af[m] = *(const bf16x8*)(sa + m * 2048 + (((ks * 4 + fq) ^ swz) << 4));
; #pragma unroll
;             for (int n = 0; n < 2; ++n) bf[n] = *(const bf16x8*)(sb + n * 2048 + (((ks * 4 + fq) ^ swz) << 4));
; #pragma unroll
;             for (int m = 0; m < 4; ++m)
; #pragma unroll
;               for (int n = 0; n < 2; ++n)
;                 acc[m][n] = SWAP ? __builtin_amdgcn_mfma_f32_16x16x32_bf16(bf[n], af[m], acc[m][n], 0, 0, 0)
;                                  : __builtin_amdgcn_mfma_f32_16x16x32_bf16(af[m], bf[n], acc[m][n], 0, 0, 0);
;           }
.LBB0_1535:
	s_or_b64 exec, exec, s[6:7]
	v_readfirstlane_b32 s6, v56
	s_waitcnt vmcnt(0)
	s_barrier
	v_lshl_add_u64 v[4:5], v[46:47], 0, s[40:41]
	s_mov_b32 m0, s6
	v_or_b32_e32 v2, 0x180, v38
	v_readfirstlane_b32 s6, v67
	global_load_lds_dwordx4 v[4:5], off
	v_lshl_add_u64 v[4:5], v[2:3], 1, s[18:19]
	s_mov_b32 m0, s6
	v_readfirstlane_b32 s6, v68
	global_load_lds_dwordx4 v[4:5], off
	v_lshl_add_u64 v[4:5], v[48:49], 0, s[40:41]
	s_mov_b32 m0, s6
	v_or_b32_e32 v2, 0x180, v40
	v_readfirstlane_b32 s6, v69
	global_load_lds_dwordx4 v[4:5], off
	v_lshl_add_u64 v[4:5], v[2:3], 1, s[18:19]
	s_mov_b32 m0, s6
	v_readfirstlane_b32 s6, v70
	v_lshl_add_u64 v[4:5], v[50:51], 0, s[40:41]
	s_mov_b32 m0, s6
	v_or_b32_e32 v2, 0x180, v42
	v_readfirstlane_b32 s6, v71
	global_load_lds_dwordx4 v[4:5], off
	v_lshl_add_u64 v[4:5], v[2:3], 1, s[18:19]
	s_mov_b32 m0, s6
	v_readfirstlane_b32 s6, v72
	v_lshl_add_u64 v[4:5], v[52:53], 0, s[40:41]
	s_mov_b32 m0, s6
	v_or_b32_e32 v2, 0x180, v44
	v_readfirstlane_b32 s6, v73
	global_load_lds_dwordx4 v[4:5], off
	v_lshl_add_u64 v[4:5], v[2:3], 1, s[18:19]
	s_mov_b32 m0, s6
	s_nop 0
	s_and_saveexec_b64 s[6:7], s[4:5]
	s_cbranch_execz .LBB0_1537
	ds_read_b128 v[94:97], v87
	ds_read_b128 v[98:101], v87 offset:2048
	ds_read_b128 v[102:105], v86
	ds_read_b128 v[106:109], v86 offset:2048
	s_waitcnt lgkmcnt(0)
	v_mfma_f32_16x16x32_bf16 v[34:37], v[94:97], v[102:105], v[34:37]
	v_mfma_f32_16x16x32_bf16 v[30:33], v[98:101], v[102:105], v[30:33]
	v_mfma_f32_16x16x32_bf16 v[26:29], v[94:97], v[106:109], v[26:29]
	v_mfma_f32_16x16x32_bf16 v[22:25], v[98:101], v[106:109], v[22:25]
	ds_read_b128 v[102:105], v86 offset:4096
	ds_read_b128 v[106:109], v86 offset:6144
	s_waitcnt lgkmcnt(0)
	v_mfma_f32_16x16x32_bf16 v[18:21], v[94:97], v[102:105], v[18:21]
	v_mfma_f32_16x16x32_bf16 v[10:13], v[94:97], v[106:109], v[10:13]
	ds_read_b128 v[94:97], v89
	v_mfma_f32_16x16x32_bf16 v[14:17], v[98:101], v[102:105], v[14:17]
	v_mfma_f32_16x16x32_bf16 v[4:7], v[98:101], v[106:109], v[6:9]
	ds_read_b128 v[98:101], v89 offset:2048
	ds_read_b128 v[102:105], v88
	ds_read_b128 v[106:109], v88 offset:2048
	s_waitcnt lgkmcnt(0)
	v_mfma_f32_16x16x32_bf16 v[34:37], v[94:97], v[102:105], v[34:37]
	v_mfma_f32_16x16x32_bf16 v[30:33], v[98:101], v[102:105], v[30:33]
	v_mfma_f32_16x16x32_bf16 v[26:29], v[94:97], v[106:109], v[26:29]
	v_mfma_f32_16x16x32_bf16 v[22:25], v[98:101], v[106:109], v[22:25]
	ds_read_b128 v[102:105], v88 offset:4096
	ds_read_b128 v[106:109], v88 offset:6144
	s_waitcnt lgkmcnt(0)
	v_mfma_f32_16x16x32_bf16 v[18:21], v[94:97], v[102:105], v[18:21]
	v_mfma_f32_16x16x32_bf16 v[14:17], v[98:101], v[102:105], v[14:17]
	v_mfma_f32_16x16x32_bf16 v[10:13], v[94:97], v[106:109], v[10:13]
	v_mfma_f32_16x16x32_bf16 v[6:9], v[98:101], v[106:109], v[4:7]
.LBB0_1537:
	s_or_b64 exec, exec, s[6:7]
	v_readfirstlane_b32 s6, v74
	s_waitcnt vmcnt(0)
	s_barrier
	v_lshl_add_u64 v[4:5], v[46:47], 0, s[42:43]
	s_mov_b32 m0, s6
	v_or_b32_e32 v2, 0x1c0, v38
	v_readfirstlane_b32 s6, v75
	global_load_lds_dwordx4 v[4:5], off
	v_lshl_add_u64 v[4:5], v[2:3], 1, s[18:19]
	s_mov_b32 m0, s6
	v_readfirstlane_b32 s6, v76
	global_load_lds_dwordx4 v[4:5], off
	v_lshl_add_u64 v[4:5], v[48:49], 0, s[42:43]
	s_mov_b32 m0, s6
	v_or_b32_e32 v2, 0x1c0, v40
	v_readfirstlane_b32 s6, v77
	global_load_lds_dwordx4 v[4:5], off
	v_lshl_add_u64 v[4:5], v[2:3], 1, s[18:19]
	s_mov_b32 m0, s6
	v_readfirstlane_b32 s6, v78
	v_lshl_add_u64 v[4:5], v[50:51], 0, s[42:43]
	s_mov_b32 m0, s6
	v_or_b32_e32 v2, 0x1c0, v42
	v_readfirstlane_b32 s6, v79
	global_load_lds_dwordx4 v[4:5], off
	v_lshl_add_u64 v[4:5], v[2:3], 1, s[18:19]
	s_mov_b32 m0, s6
	v_readfirstlane_b32 s6, v80
	v_lshl_add_u64 v[4:5], v[52:53], 0, s[42:43]
	s_mov_b32 m0, s6
	v_or_b32_e32 v2, 0x1c0, v44
	v_readfirstlane_b32 s6, v81
	global_load_lds_dwordx4 v[4:5], off
	v_lshl_add_u64 v[4:5], v[2:3], 1, s[18:19]
	s_mov_b32 m0, s6
	s_nop 0
	s_and_saveexec_b64 s[6:7], s[4:5]
	s_cbranch_execz .LBB0_1539
	ds_read_b128 v[94:97], v83 offset:32768
	ds_read_b128 v[98:101], v83 offset:34816
	ds_read_b128 v[102:105], v82
	ds_read_b128 v[106:109], v82 offset:2048
	s_waitcnt lgkmcnt(0)
	v_mfma_f32_16x16x32_bf16 v[34:37], v[94:97], v[102:105], v[34:37]
	v_mfma_f32_16x16x32_bf16 v[30:33], v[98:101], v[102:105], v[30:33]
	v_mfma_f32_16x16x32_bf16 v[26:29], v[94:97], v[106:109], v[26:29]
	v_mfma_f32_16x16x32_bf16 v[22:25], v[98:101], v[106:109], v[22:25]
	ds_read_b128 v[102:105], v82 offset:4096
	ds_read_b128 v[106:109], v82 offset:6144
	s_waitcnt lgkmcnt(0)
	v_mfma_f32_16x16x32_bf16 v[18:21], v[94:97], v[102:105], v[18:21]
	v_mfma_f32_16x16x32_bf16 v[10:13], v[94:97], v[106:109], v[10:13]
	ds_read_b128 v[94:97], v85 offset:32768
	v_mfma_f32_16x16x32_bf16 v[14:17], v[98:101], v[102:105], v[14:17]
	v_mfma_f32_16x16x32_bf16 v[4:7], v[98:101], v[106:109], v[6:9]
	ds_read_b128 v[98:101], v85 offset:34816
	ds_read_b128 v[102:105], v84
	ds_read_b128 v[106:109], v84 offset:2048
	s_waitcnt lgkmcnt(0)
	v_mfma_f32_16x16x32_bf16 v[34:37], v[94:97], v[102:105], v[34:37]
	v_mfma_f32_16x16x32_bf16 v[30:33], v[98:101], v[102:105], v[30:33]
	v_mfma_f32_16x16x32_bf16 v[26:29], v[94:97], v[106:109], v[26:29]
	v_mfma_f32_16x16x32_bf16 v[22:25], v[98:101], v[106:109], v[22:25]
	ds_read_b128 v[102:105], v84 offset:4096
	ds_read_b128 v[106:109], v84 offset:6144
	s_waitcnt lgkmcnt(0)
	v_mfma_f32_16x16x32_bf16 v[18:21], v[94:97], v[102:105], v[18:21]
	v_mfma_f32_16x16x32_bf16 v[14:17], v[98:101], v[102:105], v[14:17]
	v_mfma_f32_16x16x32_bf16 v[10:13], v[94:97], v[106:109], v[10:13]
	v_mfma_f32_16x16x32_bf16 v[6:9], v[98:101], v[106:109], v[4:7]
; #define GLDS16(gp, lp) __builtin_amdgcn_global_load_lds((const unsigned*)(gp), (__attribute__((address_space(3))) unsigned*)(lp), 16, 0, 0)
; template <bool SWAP, class Epi, bool THIN = false> ...
;     ...
;     for (int st = 0; st < ns; ++st) {
;       asm volatile("s_waitcnt vmcnt(0)" ::: "memory");
;       __builtin_amdgcn_s_barrier();
;       asm volatile("" ::: "memory");
;       if (st + 1 < ns) {
;         char* nb = smem + ((st + 1) & 1) * 65536;
;         const int ko = (st + 1) * 64;
; #pragma unroll
;         for (int i = 0; i < 4; ++i) { GLDS16(A + (size_t)(ap[i] + ko), nb + tid * 16 + i * 8192); GLDS16(Bt + (size_t)(bp[i] + ko), nb + 32768 + tid * 16 + i * 8192); }
;       }
;       const char* sa = smem + (st & 1) * 65536 + (wr * 64 + fr) * 128;
;       const char* sb = smem + (st & 1) * 65536 + 32768 + (wc * 128 + fr) * 128;
;       if constexpr (THIN) {
;         if (wc == 0) {
; #pragma unroll
;           for (int ks = 0; ks < 2; ++ks) {
;             bf16x8 af[4], bf[2];
; #pragma unroll
;             for (int m = 0; m < 4; ++m) af[m] = *(const bf16x8*)(sa + m * 2048 + (((ks * 4 + fq) ^ swz) << 4));
; #pragma unroll
;             for (int n = 0; n < 2; ++n) bf[n] = *(const bf16x8*)(sb + n * 2048 + (((ks * 4 + fq) ^ swz) << 4));
; #pragma unroll
;             for (int m = 0; m < 4; ++m)
; #pragma unroll
;               for (int n = 0; n < 2; ++n)
;                 acc[m][n] = SWAP ? __builtin_amdgcn_mfma_f32_16x16x32_bf16(bf[n], af[m], acc[m][n], 0, 0, 0)
;                                  : __builtin_amdgcn_mfma_f32_16x16x32_bf16(af[m], bf[n], acc[m][n], 0, 0, 0);
;           }
.LBB0_1539:
	s_or_b64 exec, exec, s[6:7]
	v_readfirstlane_b32 s6, v56
	s_waitcnt vmcnt(0)
	s_barrier
	v_lshl_add_u64 v[4:5], v[46:47], 0, s[44:45]
	s_mov_b32 m0, s6
	v_or_b32_e32 v2, 0x200, v38
	v_readfirstlane_b32 s6, v67
	global_load_lds_dwordx4 v[4:5], off
	v_lshl_add_u64 v[4:5], v[2:3], 1, s[18:19]
	s_mov_b32 m0, s6
	v_readfirstlane_b32 s6, v68
	global_load_lds_dwordx4 v[4:5], off
	v_lshl_add_u64 v[4:5], v[48:49], 0, s[44:45]
	s_mov_b32 m0, s6
	v_or_b32_e32 v2, 0x200, v40
	v_readfirstlane_b32 s6, v69
	global_load_lds_dwordx4 v[4:5], off
	v_lshl_add_u64 v[4:5], v[2:3], 1, s[18:19]
	s_mov_b32 m0, s6
	v_readfirstlane_b32 s6, v70
	v_lshl_add_u64 v[4:5], v[50:51], 0, s[44:45]
	s_mov_b32 m0, s6
	v_or_b32_e32 v2, 0x200, v42
	v_readfirstlane_b32 s6, v71
	global_load_lds_dwordx4 v[4:5], off
	v_lshl_add_u64 v[4:5], v[2:3], 1, s[18:19]
	s_mov_b32 m0, s6
	v_readfirstlane_b32 s6, v72
	v_lshl_add_u64 v[4:5], v[52:53], 0, s[44:45]
	s_mov_b32 m0, s6
	v_or_b32_e32 v2, 0x200, v44
	v_readfirstlane_b32 s6, v73
	global_load_lds_dwordx4 v[4:5], off
	v_lshl_add_u64 v[4:5], v[2:3], 1, s[18:19]
	s_mov_b32 m0, s6
	s_nop 0
	s_and_saveexec_b64 s[6:7], s[4:5]
	s_cbranch_execz .LBB0_1541
	ds_read_b128 v[94:97], v87
	ds_read_b128 v[98:101], v87 offset:2048
	ds_read_b128 v[102:105], v86
	ds_read_b128 v[106:109], v86 offset:2048
	s_waitcnt lgkmcnt(0)
	v_mfma_f32_16x16x32_bf16 v[34:37], v[94:97], v[102:105], v[34:37]
	v_mfma_f32_16x16x32_bf16 v[30:33], v[98:101], v[102:105], v[30:33]
	v_mfma_f32_16x16x32_bf16 v[26:29], v[94:97], v[106:109], v[26:29]
	v_mfma_f32_16x16x32_bf16 v[22:25], v[98:101], v[106:109], v[22:25]
	ds_read_b128 v[102:105], v86 offset:4096
	ds_read_b128 v[106:109], v86 offset:6144
	s_waitcnt lgkmcnt(0)
	v_mfma_f32_16x16x32_bf16 v[18:21], v[94:97], v[102:105], v[18:21]
	v_mfma_f32_16x16x32_bf16 v[10:13], v[94:97], v[106:109], v[10:13]
	ds_read_b128 v[94:97], v89
	v_mfma_f32_16x16x32_bf16 v[14:17], v[98:101], v[102:105], v[14:17]
	v_mfma_f32_16x16x32_bf16 v[4:7], v[98:101], v[106:109], v[6:9]
	ds_read_b128 v[98:101], v89 offset:2048
	ds_read_b128 v[102:105], v88
	ds_read_b128 v[106:109], v88 offset:2048
	s_waitcnt lgkmcnt(0)
	v_mfma_f32_16x16x32_bf16 v[34:37], v[94:97], v[102:105], v[34:37]
	v_mfma_f32_16x16x32_bf16 v[30:33], v[98:101], v[102:105], v[30:33]
	v_mfma_f32_16x16x32_bf16 v[26:29], v[94:97], v[106:109], v[26:29]
	v_mfma_f32_16x16x32_bf16 v[22:25], v[98:101], v[106:109], v[22:25]
	ds_read_b128 v[102:105], v88 offset:4096
	ds_read_b128 v[106:109], v88 offset:6144
	s_waitcnt lgkmcnt(0)
	v_mfma_f32_16x16x32_bf16 v[18:21], v[94:97], v[102:105], v[18:21]
	v_mfma_f32_16x16x32_bf16 v[14:17], v[98:101], v[102:105], v[14:17]
	v_mfma_f32_16x16x32_bf16 v[10:13], v[94:97], v[106:109], v[10:13]
	v_mfma_f32_16x16x32_bf16 v[6:9], v[98:101], v[106:109], v[4:7]
.LBB0_1541:
	s_or_b64 exec, exec, s[6:7]
	v_readfirstlane_b32 s6, v74
	s_waitcnt vmcnt(0)
	s_barrier
	v_lshl_add_u64 v[4:5], v[46:47], 0, s[48:49]
	s_mov_b32 m0, s6
	v_or_b32_e32 v2, 0x240, v38
	v_readfirstlane_b32 s6, v75
	global_load_lds_dwordx4 v[4:5], off
	v_lshl_add_u64 v[4:5], v[2:3], 1, s[18:19]
	s_mov_b32 m0, s6
	v_readfirstlane_b32 s6, v76
	global_load_lds_dwordx4 v[4:5], off
	v_lshl_add_u64 v[4:5], v[48:49], 0, s[48:49]
	s_mov_b32 m0, s6
	v_or_b32_e32 v2, 0x240, v40
	v_readfirstlane_b32 s6, v77
	global_load_lds_dwordx4 v[4:5], off
	v_lshl_add_u64 v[4:5], v[2:3], 1, s[18:19]
	s_mov_b32 m0, s6
	v_readfirstlane_b32 s6, v78
	v_lshl_add_u64 v[4:5], v[50:51], 0, s[48:49]
	s_mov_b32 m0, s6
	v_or_b32_e32 v2, 0x240, v42
	v_readfirstlane_b32 s6, v79
	global_load_lds_dwordx4 v[4:5], off
	v_lshl_add_u64 v[4:5], v[2:3], 1, s[18:19]
	s_mov_b32 m0, s6
	v_readfirstlane_b32 s6, v80
	v_lshl_add_u64 v[4:5], v[52:53], 0, s[48:49]
	s_mov_b32 m0, s6
	v_or_b32_e32 v2, 0x240, v44
	v_readfirstlane_b32 s6, v81
	global_load_lds_dwordx4 v[4:5], off
	v_lshl_add_u64 v[4:5], v[2:3], 1, s[18:19]
	s_mov_b32 m0, s6
	s_nop 0
	s_and_saveexec_b64 s[6:7], s[4:5]
	s_cbranch_execz .LBB0_1543
	ds_read_b128 v[94:97], v83 offset:32768
	ds_read_b128 v[98:101], v83 offset:34816
	ds_read_b128 v[102:105], v82
	ds_read_b128 v[106:109], v82 offset:2048
	s_waitcnt lgkmcnt(0)
	v_mfma_f32_16x16x32_bf16 v[34:37], v[94:97], v[102:105], v[34:37]
	v_mfma_f32_16x16x32_bf16 v[30:33], v[98:101], v[102:105], v[30:33]
	v_mfma_f32_16x16x32_bf16 v[26:29], v[94:97], v[106:109], v[26:29]
	v_mfma_f32_16x16x32_bf16 v[22:25], v[98:101], v[106:109], v[22:25]
	ds_read_b128 v[102:105], v82 offset:4096
	ds_read_b128 v[106:109], v82 offset:6144
	s_waitcnt lgkmcnt(0)
	v_mfma_f32_16x16x32_bf16 v[18:21], v[94:97], v[102:105], v[18:21]
	v_mfma_f32_16x16x32_bf16 v[10:13], v[94:97], v[106:109], v[10:13]
	ds_read_b128 v[94:97], v85 offset:32768
	v_mfma_f32_16x16x32_bf16 v[14:17], v[98:101], v[102:105], v[14:17]
	v_mfma_f32_16x16x32_bf16 v[4:7], v[98:101], v[106:109], v[6:9]
	ds_read_b128 v[98:101], v85 offset:34816
	ds_read_b128 v[102:105], v84
	ds_read_b128 v[106:109], v84 offset:2048
	s_waitcnt lgkmcnt(0)
	v_mfma_f32_16x16x32_bf16 v[34:37], v[94:97], v[102:105], v[34:37]
	v_mfma_f32_16x16x32_bf16 v[30:33], v[98:101], v[102:105], v[30:33]
	v_mfma_f32_16x16x32_bf16 v[26:29], v[94:97], v[106:109], v[26:29]
	v_mfma_f32_16x16x32_bf16 v[22:25], v[98:101], v[106:109], v[22:25]
	ds_read_b128 v[102:105], v84 offset:4096
	ds_read_b128 v[106:109], v84 offset:6144
	s_waitcnt lgkmcnt(0)
	v_mfma_f32_16x16x32_bf16 v[18:21], v[94:97], v[102:105], v[18:21]
	v_mfma_f32_16x16x32_bf16 v[14:17], v[98:101], v[102:105], v[14:17]
	v_mfma_f32_16x16x32_bf16 v[10:13], v[94:97], v[106:109], v[10:13]
	v_mfma_f32_16x16x32_bf16 v[6:9], v[98:101], v[106:109], v[4:7]
; #define GLDS16(gp, lp) __builtin_amdgcn_global_load_lds((const unsigned*)(gp), (__attribute__((address_space(3))) unsigned*)(lp), 16, 0, 0)
; template <bool SWAP, class Epi, bool THIN = false> ...
;     ...
;     for (int st = 0; st < ns; ++st) {
;       asm volatile("s_waitcnt vmcnt(0)" ::: "memory");
;       __builtin_amdgcn_s_barrier();
;       asm volatile("" ::: "memory");
;       if (st + 1 < ns) {
;         char* nb = smem + ((st + 1) & 1) * 65536;
;         const int ko = (st + 1) * 64;
; #pragma unroll
;         for (int i = 0; i < 4; ++i) { GLDS16(A + (size_t)(ap[i] + ko), nb + tid * 16 + i * 8192); GLDS16(Bt + (size_t)(bp[i] + ko), nb + 32768 + tid * 16 + i * 8192); }
;       }
;       const char* sa = smem + (st & 1) * 65536 + (wr * 64 + fr) * 128;
;       const char* sb = smem + (st & 1) * 65536 + 32768 + (wc * 128 + fr) * 128;
;       if constexpr (THIN) {
;         if (wc == 0) {
; #pragma unroll
;           for (int ks = 0; ks < 2; ++ks) {
;             bf16x8 af[4], bf[2];
; #pragma unroll
;             for (int m = 0; m < 4; ++m) af[m] = *(const bf16x8*)(sa + m * 2048 + (((ks * 4 + fq) ^ swz) << 4));
; #pragma unroll
;             for (int n = 0; n < 2; ++n) bf[n] = *(const bf16x8*)(sb + n * 2048 + (((ks * 4 + fq) ^ swz) << 4));
; #pragma unroll
;             for (int m = 0; m < 4; ++m)
; #pragma unroll
;               for (int n = 0; n < 2; ++n)
;                 acc[m][n] = SWAP ? __builtin_amdgcn_mfma_f32_16x16x32_bf16(bf[n], af[m], acc[m][n], 0, 0, 0)
;                                  : __builtin_amdgcn_mfma_f32_16x16x32_bf16(af[m], bf[n], acc[m][n], 0, 0, 0);
;           }
.LBB0_1543:
	s_or_b64 exec, exec, s[6:7]
	v_readfirstlane_b32 s6, v56
	s_waitcnt vmcnt(0)
	s_barrier
	v_lshl_add_u64 v[4:5], v[46:47], 0, s[50:51]
	s_mov_b32 m0, s6
	v_or_b32_e32 v2, 0x280, v38
	v_readfirstlane_b32 s6, v67
	global_load_lds_dwordx4 v[4:5], off
	v_lshl_add_u64 v[4:5], v[2:3], 1, s[18:19]
	s_mov_b32 m0, s6
	v_readfirstlane_b32 s6, v68
	global_load_lds_dwordx4 v[4:5], off
	v_lshl_add_u64 v[4:5], v[48:49], 0, s[50:51]
	s_mov_b32 m0, s6
	v_or_b32_e32 v2, 0x280, v40
	v_readfirstlane_b32 s6, v69
	global_load_lds_dwordx4 v[4:5], off
	v_lshl_add_u64 v[4:5], v[2:3], 1, s[18:19]
	s_mov_b32 m0, s6
	v_readfirstlane_b32 s6, v70
	v_lshl_add_u64 v[4:5], v[50:51], 0, s[50:51]
	s_mov_b32 m0, s6
	v_or_b32_e32 v2, 0x280, v42
	v_readfirstlane_b32 s6, v71
	global_load_lds_dwordx4 v[4:5], off
	v_lshl_add_u64 v[4:5], v[2:3], 1, s[18:19]
	s_mov_b32 m0, s6
	v_readfirstlane_b32 s6, v72
	v_lshl_add_u64 v[4:5], v[52:53], 0, s[50:51]
	s_mov_b32 m0, s6
	v_or_b32_e32 v2, 0x280, v44
	v_readfirstlane_b32 s6, v73
	global_load_lds_dwordx4 v[4:5], off
	v_lshl_add_u64 v[4:5], v[2:3], 1, s[18:19]
	s_mov_b32 m0, s6
	s_nop 0
	s_and_saveexec_b64 s[6:7], s[4:5]
	s_cbranch_execz .LBB0_1545
	ds_read_b128 v[94:97], v87
	ds_read_b128 v[98:101], v87 offset:2048
	ds_read_b128 v[102:105], v86
	ds_read_b128 v[106:109], v86 offset:2048
	s_waitcnt lgkmcnt(0)
	v_mfma_f32_16x16x32_bf16 v[34:37], v[94:97], v[102:105], v[34:37]
	v_mfma_f32_16x16x32_bf16 v[30:33], v[98:101], v[102:105], v[30:33]
	v_mfma_f32_16x16x32_bf16 v[26:29], v[94:97], v[106:109], v[26:29]
	v_mfma_f32_16x16x32_bf16 v[22:25], v[98:101], v[106:109], v[22:25]
	ds_read_b128 v[102:105], v86 offset:4096
	ds_read_b128 v[106:109], v86 offset:6144
	s_waitcnt lgkmcnt(0)
	v_mfma_f32_16x16x32_bf16 v[18:21], v[94:97], v[102:105], v[18:21]
	v_mfma_f32_16x16x32_bf16 v[10:13], v[94:97], v[106:109], v[10:13]
	ds_read_b128 v[94:97], v89
	v_mfma_f32_16x16x32_bf16 v[14:17], v[98:101], v[102:105], v[14:17]
	v_mfma_f32_16x16x32_bf16 v[4:7], v[98:101], v[106:109], v[6:9]
	ds_read_b128 v[98:101], v89 offset:2048
	ds_read_b128 v[102:105], v88
	ds_read_b128 v[106:109], v88 offset:2048
	s_waitcnt lgkmcnt(0)
	v_mfma_f32_16x16x32_bf16 v[34:37], v[94:97], v[102:105], v[34:37]
	v_mfma_f32_16x16x32_bf16 v[30:33], v[98:101], v[102:105], v[30:33]
	v_mfma_f32_16x16x32_bf16 v[26:29], v[94:97], v[106:109], v[26:29]
	v_mfma_f32_16x16x32_bf16 v[22:25], v[98:101], v[106:109], v[22:25]
	ds_read_b128 v[102:105], v88 offset:4096
	ds_read_b128 v[106:109], v88 offset:6144
	s_waitcnt lgkmcnt(0)
	v_mfma_f32_16x16x32_bf16 v[18:21], v[94:97], v[102:105], v[18:21]
	v_mfma_f32_16x16x32_bf16 v[14:17], v[98:101], v[102:105], v[14:17]
	v_mfma_f32_16x16x32_bf16 v[10:13], v[94:97], v[106:109], v[10:13]
	v_mfma_f32_16x16x32_bf16 v[6:9], v[98:101], v[106:109], v[4:7]
.LBB0_1545:
	s_or_b64 exec, exec, s[6:7]
	v_readfirstlane_b32 s6, v74
	s_waitcnt vmcnt(0)
	s_barrier
	v_lshl_add_u64 v[4:5], v[46:47], 0, s[56:57]
	s_mov_b32 m0, s6
	v_or_b32_e32 v2, 0x2c0, v38
	v_readfirstlane_b32 s6, v75
	global_load_lds_dwordx4 v[4:5], off
	v_lshl_add_u64 v[4:5], v[2:3], 1, s[18:19]
	s_mov_b32 m0, s6
	v_readfirstlane_b32 s6, v76
	global_load_lds_dwordx4 v[4:5], off
	v_lshl_add_u64 v[4:5], v[48:49], 0, s[56:57]
	s_mov_b32 m0, s6
	v_or_b32_e32 v2, 0x2c0, v40
	v_readfirstlane_b32 s6, v77
	global_load_lds_dwordx4 v[4:5], off
	v_lshl_add_u64 v[4:5], v[2:3], 1, s[18:19]
	s_mov_b32 m0, s6
	v_readfirstlane_b32 s6, v78
	v_lshl_add_u64 v[4:5], v[50:51], 0, s[56:57]
	s_mov_b32 m0, s6
	v_or_b32_e32 v2, 0x2c0, v42
	v_readfirstlane_b32 s6, v79
	global_load_lds_dwordx4 v[4:5], off
	v_lshl_add_u64 v[4:5], v[2:3], 1, s[18:19]
	s_mov_b32 m0, s6
	v_readfirstlane_b32 s6, v80
	v_lshl_add_u64 v[4:5], v[52:53], 0, s[56:57]
	s_mov_b32 m0, s6
	v_or_b32_e32 v2, 0x2c0, v44
	v_readfirstlane_b32 s6, v81
	global_load_lds_dwordx4 v[4:5], off
	v_lshl_add_u64 v[4:5], v[2:3], 1, s[18:19]
	s_mov_b32 m0, s6
	s_nop 0
	s_and_saveexec_b64 s[6:7], s[4:5]
	s_cbranch_execz .LBB0_1547
	ds_read_b128 v[94:97], v83 offset:32768
	ds_read_b128 v[98:101], v83 offset:34816
	ds_read_b128 v[102:105], v82
	ds_read_b128 v[106:109], v82 offset:2048
	s_waitcnt lgkmcnt(0)
	v_mfma_f32_16x16x32_bf16 v[34:37], v[94:97], v[102:105], v[34:37]
	v_mfma_f32_16x16x32_bf16 v[30:33], v[98:101], v[102:105], v[30:33]
	v_mfma_f32_16x16x32_bf16 v[26:29], v[94:97], v[106:109], v[26:29]
	v_mfma_f32_16x16x32_bf16 v[22:25], v[98:101], v[106:109], v[22:25]
	ds_read_b128 v[102:105], v82 offset:4096
	ds_read_b128 v[106:109], v82 offset:6144
	s_waitcnt lgkmcnt(0)
	v_mfma_f32_16x16x32_bf16 v[18:21], v[94:97], v[102:105], v[18:21]
	v_mfma_f32_16x16x32_bf16 v[10:13], v[94:97], v[106:109], v[10:13]
	ds_read_b128 v[94:97], v85 offset:32768
	v_mfma_f32_16x16x32_bf16 v[14:17], v[98:101], v[102:105], v[14:17]
	v_mfma_f32_16x16x32_bf16 v[4:7], v[98:101], v[106:109], v[6:9]
	ds_read_b128 v[98:101], v85 offset:34816
	ds_read_b128 v[102:105], v84
	ds_read_b128 v[106:109], v84 offset:2048
	s_waitcnt lgkmcnt(0)
	v_mfma_f32_16x16x32_bf16 v[34:37], v[94:97], v[102:105], v[34:37]
	v_mfma_f32_16x16x32_bf16 v[30:33], v[98:101], v[102:105], v[30:33]
	v_mfma_f32_16x16x32_bf16 v[26:29], v[94:97], v[106:109], v[26:29]
	v_mfma_f32_16x16x32_bf16 v[22:25], v[98:101], v[106:109], v[22:25]
	ds_read_b128 v[102:105], v84 offset:4096
	ds_read_b128 v[106:109], v84 offset:6144
	s_waitcnt lgkmcnt(0)
	v_mfma_f32_16x16x32_bf16 v[18:21], v[94:97], v[102:105], v[18:21]
	v_mfma_f32_16x16x32_bf16 v[14:17], v[98:101], v[102:105], v[14:17]
	v_mfma_f32_16x16x32_bf16 v[10:13], v[94:97], v[106:109], v[10:13]
	v_mfma_f32_16x16x32_bf16 v[6:9], v[98:101], v[106:109], v[4:7]
; #define GLDS16(gp, lp) __builtin_amdgcn_global_load_lds((const unsigned*)(gp), (__attribute__((address_space(3))) unsigned*)(lp), 16, 0, 0)
; template <bool SWAP, class Epi, bool THIN = false> ...
;     ...
;     for (int st = 0; st < ns; ++st) {
;       asm volatile("s_waitcnt vmcnt(0)" ::: "memory");
;       __builtin_amdgcn_s_barrier();
;       asm volatile("" ::: "memory");
;       if (st + 1 < ns) {
;         char* nb = smem + ((st + 1) & 1) * 65536;
;         const int ko = (st + 1) * 64;
; #pragma unroll
;         for (int i = 0; i < 4; ++i) { GLDS16(A + (size_t)(ap[i] + ko), nb + tid * 16 + i * 8192); GLDS16(Bt + (size_t)(bp[i] + ko), nb + 32768 + tid * 16 + i * 8192); }
;       }
;       const char* sa = smem + (st & 1) * 65536 + (wr * 64 + fr) * 128;
;       const char* sb = smem + (st & 1) * 65536 + 32768 + (wc * 128 + fr) * 128;
;       if constexpr (THIN) {
;         if (wc == 0) {
; #pragma unroll
;           for (int ks = 0; ks < 2; ++ks) {
;             bf16x8 af[4], bf[2];
; #pragma unroll
;             for (int m = 0; m < 4; ++m) af[m] = *(const bf16x8*)(sa + m * 2048 + (((ks * 4 + fq) ^ swz) << 4));
; #pragma unroll
;             for (int n = 0; n < 2; ++n) bf[n] = *(const bf16x8*)(sb + n * 2048 + (((ks * 4 + fq) ^ swz) << 4));
; #pragma unroll
;             for (int m = 0; m < 4; ++m)
; #pragma unroll
;               for (int n = 0; n < 2; ++n)
;                 acc[m][n] = SWAP ? __builtin_amdgcn_mfma_f32_16x16x32_bf16(bf[n], af[m], acc[m][n], 0, 0, 0)
;                                  : __builtin_amdgcn_mfma_f32_16x16x32_bf16(af[m], bf[n], acc[m][n], 0, 0, 0);
;           }
.LBB0_1547:
	s_or_b64 exec, exec, s[6:7]
	v_readfirstlane_b32 s6, v56
	s_waitcnt vmcnt(0)
	s_barrier
	v_lshl_add_u64 v[4:5], v[46:47], 0, s[58:59]
	s_mov_b32 m0, s6
	v_or_b32_e32 v2, 0x300, v38
	v_readfirstlane_b32 s6, v67
	global_load_lds_dwordx4 v[4:5], off
	v_lshl_add_u64 v[4:5], v[2:3], 1, s[18:19]
	s_mov_b32 m0, s6
	v_readfirstlane_b32 s6, v68
	global_load_lds_dwordx4 v[4:5], off
	v_lshl_add_u64 v[4:5], v[48:49], 0, s[58:59]
	s_mov_b32 m0, s6
	v_or_b32_e32 v2, 0x300, v40
	v_readfirstlane_b32 s6, v69
	global_load_lds_dwordx4 v[4:5], off
	v_lshl_add_u64 v[4:5], v[2:3], 1, s[18:19]
	s_mov_b32 m0, s6
	v_readfirstlane_b32 s6, v70
	v_lshl_add_u64 v[4:5], v[50:51], 0, s[58:59]
	s_mov_b32 m0, s6
	v_or_b32_e32 v2, 0x300, v42
	v_readfirstlane_b32 s6, v71
	global_load_lds_dwordx4 v[4:5], off
	v_lshl_add_u64 v[4:5], v[2:3], 1, s[18:19]
	s_mov_b32 m0, s6
	v_readfirstlane_b32 s6, v72
	v_lshl_add_u64 v[4:5], v[52:53], 0, s[58:59]
	s_mov_b32 m0, s6
	v_or_b32_e32 v2, 0x300, v44
	v_readfirstlane_b32 s6, v73
	global_load_lds_dwordx4 v[4:5], off
	v_lshl_add_u64 v[4:5], v[2:3], 1, s[18:19]
	s_mov_b32 m0, s6
	s_nop 0
	s_and_saveexec_b64 s[6:7], s[4:5]
	s_cbranch_execz .LBB0_1549
	ds_read_b128 v[94:97], v87
	ds_read_b128 v[98:101], v87 offset:2048
	ds_read_b128 v[102:105], v86
	ds_read_b128 v[106:109], v86 offset:2048
	s_waitcnt lgkmcnt(0)
	v_mfma_f32_16x16x32_bf16 v[34:37], v[94:97], v[102:105], v[34:37]
	v_mfma_f32_16x16x32_bf16 v[30:33], v[98:101], v[102:105], v[30:33]
	v_mfma_f32_16x16x32_bf16 v[26:29], v[94:97], v[106:109], v[26:29]
	v_mfma_f32_16x16x32_bf16 v[22:25], v[98:101], v[106:109], v[22:25]
	ds_read_b128 v[102:105], v86 offset:4096
	ds_read_b128 v[106:109], v86 offset:6144
	s_waitcnt lgkmcnt(0)
	v_mfma_f32_16x16x32_bf16 v[18:21], v[94:97], v[102:105], v[18:21]
	v_mfma_f32_16x16x32_bf16 v[10:13], v[94:97], v[106:109], v[10:13]
	ds_read_b128 v[94:97], v89
	v_mfma_f32_16x16x32_bf16 v[14:17], v[98:101], v[102:105], v[14:17]
	v_mfma_f32_16x16x32_bf16 v[4:7], v[98:101], v[106:109], v[6:9]
	ds_read_b128 v[98:101], v89 offset:2048
	ds_read_b128 v[102:105], v88
	ds_read_b128 v[106:109], v88 offset:2048
	s_waitcnt lgkmcnt(0)
	v_mfma_f32_16x16x32_bf16 v[34:37], v[94:97], v[102:105], v[34:37]
	v_mfma_f32_16x16x32_bf16 v[30:33], v[98:101], v[102:105], v[30:33]
	v_mfma_f32_16x16x32_bf16 v[26:29], v[94:97], v[106:109], v[26:29]
	v_mfma_f32_16x16x32_bf16 v[22:25], v[98:101], v[106:109], v[22:25]
	ds_read_b128 v[102:105], v88 offset:4096
	ds_read_b128 v[106:109], v88 offset:6144
	s_waitcnt lgkmcnt(0)
	v_mfma_f32_16x16x32_bf16 v[18:21], v[94:97], v[102:105], v[18:21]
	v_mfma_f32_16x16x32_bf16 v[14:17], v[98:101], v[102:105], v[14:17]
	v_mfma_f32_16x16x32_bf16 v[10:13], v[94:97], v[106:109], v[10:13]
	v_mfma_f32_16x16x32_bf16 v[6:9], v[98:101], v[106:109], v[4:7]
.LBB0_1549:
	s_or_b64 exec, exec, s[6:7]
	v_readfirstlane_b32 s6, v74
	s_waitcnt vmcnt(0)
	s_barrier
	v_lshl_add_u64 v[4:5], v[46:47], 0, s[60:61]
	s_mov_b32 m0, s6
	v_or_b32_e32 v2, 0x340, v38
	v_readfirstlane_b32 s6, v75
	global_load_lds_dwordx4 v[4:5], off
	v_lshl_add_u64 v[4:5], v[2:3], 1, s[18:19]
	s_mov_b32 m0, s6
	v_readfirstlane_b32 s6, v76
	global_load_lds_dwordx4 v[4:5], off
	v_lshl_add_u64 v[4:5], v[48:49], 0, s[60:61]
	s_mov_b32 m0, s6
	v_or_b32_e32 v2, 0x340, v40
	v_readfirstlane_b32 s6, v77
	global_load_lds_dwordx4 v[4:5], off
	v_lshl_add_u64 v[4:5], v[2:3], 1, s[18:19]
	s_mov_b32 m0, s6
	v_readfirstlane_b32 s6, v78
	v_lshl_add_u64 v[4:5], v[50:51], 0, s[60:61]
	s_mov_b32 m0, s6
	v_or_b32_e32 v2, 0x340, v42
	v_readfirstlane_b32 s6, v79
	global_load_lds_dwordx4 v[4:5], off
	v_lshl_add_u64 v[4:5], v[2:3], 1, s[18:19]
	s_mov_b32 m0, s6
	v_readfirstlane_b32 s6, v80
	v_lshl_add_u64 v[4:5], v[52:53], 0, s[60:61]
	s_mov_b32 m0, s6
	v_or_b32_e32 v2, 0x340, v44
	v_readfirstlane_b32 s6, v81
	global_load_lds_dwordx4 v[4:5], off
	v_lshl_add_u64 v[4:5], v[2:3], 1, s[18:19]
	s_mov_b32 m0, s6
	s_nop 0
	s_and_saveexec_b64 s[6:7], s[4:5]
	s_cbranch_execz .LBB0_1551
	ds_read_b128 v[94:97], v83 offset:32768
	ds_read_b128 v[98:101], v83 offset:34816
	ds_read_b128 v[102:105], v82
	ds_read_b128 v[106:109], v82 offset:2048
	s_waitcnt lgkmcnt(0)
	v_mfma_f32_16x16x32_bf16 v[34:37], v[94:97], v[102:105], v[34:37]
	v_mfma_f32_16x16x32_bf16 v[30:33], v[98:101], v[102:105], v[30:33]
	v_mfma_f32_16x16x32_bf16 v[26:29], v[94:97], v[106:109], v[26:29]
	v_mfma_f32_16x16x32_bf16 v[22:25], v[98:101], v[106:109], v[22:25]
	ds_read_b128 v[102:105], v82 offset:4096
	ds_read_b128 v[106:109], v82 offset:6144
	s_waitcnt lgkmcnt(0)
	v_mfma_f32_16x16x32_bf16 v[18:21], v[94:97], v[102:105], v[18:21]
	v_mfma_f32_16x16x32_bf16 v[10:13], v[94:97], v[106:109], v[10:13]
	ds_read_b128 v[94:97], v85 offset:32768
	v_mfma_f32_16x16x32_bf16 v[14:17], v[98:101], v[102:105], v[14:17]
	v_mfma_f32_16x16x32_bf16 v[4:7], v[98:101], v[106:109], v[6:9]
	ds_read_b128 v[98:101], v85 offset:34816
	ds_read_b128 v[102:105], v84
	ds_read_b128 v[106:109], v84 offset:2048
	s_waitcnt lgkmcnt(0)
	v_mfma_f32_16x16x32_bf16 v[34:37], v[94:97], v[102:105], v[34:37]
	v_mfma_f32_16x16x32_bf16 v[30:33], v[98:101], v[102:105], v[30:33]
	v_mfma_f32_16x16x32_bf16 v[26:29], v[94:97], v[106:109], v[26:29]
	v_mfma_f32_16x16x32_bf16 v[22:25], v[98:101], v[106:109], v[22:25]
	ds_read_b128 v[102:105], v84 offset:4096
	ds_read_b128 v[106:109], v84 offset:6144
	s_waitcnt lgkmcnt(0)
	v_mfma_f32_16x16x32_bf16 v[18:21], v[94:97], v[102:105], v[18:21]
	v_mfma_f32_16x16x32_bf16 v[14:17], v[98:101], v[102:105], v[14:17]
	v_mfma_f32_16x16x32_bf16 v[10:13], v[94:97], v[106:109], v[10:13]
	v_mfma_f32_16x16x32_bf16 v[6:9], v[98:101], v[106:109], v[4:7]
; #define GLDS16(gp, lp) __builtin_amdgcn_global_load_lds((const unsigned*)(gp), (__attribute__((address_space(3))) unsigned*)(lp), 16, 0, 0)
; template <bool SWAP, class Epi, bool THIN = false> ...
;     ...
;     for (int st = 0; st < ns; ++st) {
;       asm volatile("s_waitcnt vmcnt(0)" ::: "memory");
;       __builtin_amdgcn_s_barrier();
;       asm volatile("" ::: "memory");
;       if (st + 1 < ns) {
;         char* nb = smem + ((st + 1) & 1) * 65536;
;         const int ko = (st + 1) * 64;
; #pragma unroll
;         for (int i = 0; i < 4; ++i) { GLDS16(A + (size_t)(ap[i] + ko), nb + tid * 16 + i * 8192); GLDS16(Bt + (size_t)(bp[i] + ko), nb + 32768 + tid * 16 + i * 8192); }
;       }
;       const char* sa = smem + (st & 1) * 65536 + (wr * 64 + fr) * 128;
;       const char* sb = smem + (st & 1) * 65536 + 32768 + (wc * 128 + fr) * 128;
;       if constexpr (THIN) {
;         if (wc == 0) {
; #pragma unroll
;           for (int ks = 0; ks < 2; ++ks) {
;             bf16x8 af[4], bf[2];
; #pragma unroll
;             for (int m = 0; m < 4; ++m) af[m] = *(const bf16x8*)(sa + m * 2048 + (((ks * 4 + fq) ^ swz) << 4));
; #pragma unroll
;             for (int n = 0; n < 2; ++n) bf[n] = *(const bf16x8*)(sb + n * 2048 + (((ks * 4 + fq) ^ swz) << 4));
; #pragma unroll
;             for (int m = 0; m < 4; ++m)
; #pragma unroll
;               for (int n = 0; n < 2; ++n)
;                 acc[m][n] = SWAP ? __builtin_amdgcn_mfma_f32_16x16x32_bf16(bf[n], af[m], acc[m][n], 0, 0, 0)
;                                  : __builtin_amdgcn_mfma_f32_16x16x32_bf16(af[m], bf[n], acc[m][n], 0, 0, 0);
;           }
.LBB0_1551:
	s_or_b64 exec, exec, s[6:7]
	v_readfirstlane_b32 s6, v56
	s_waitcnt vmcnt(0)
	s_barrier
	v_lshl_add_u64 v[4:5], v[46:47], 0, s[62:63]
	s_mov_b32 m0, s6
	v_or_b32_e32 v2, 0x380, v38
	v_readfirstlane_b32 s6, v67
	global_load_lds_dwordx4 v[4:5], off
	v_lshl_add_u64 v[4:5], v[2:3], 1, s[18:19]
	s_mov_b32 m0, s6
	v_readfirstlane_b32 s6, v68
	global_load_lds_dwordx4 v[4:5], off
	v_lshl_add_u64 v[4:5], v[48:49], 0, s[62:63]
	s_mov_b32 m0, s6
	v_or_b32_e32 v2, 0x380, v40
	v_readfirstlane_b32 s6, v69
	global_load_lds_dwordx4 v[4:5], off
	v_lshl_add_u64 v[4:5], v[2:3], 1, s[18:19]
	s_mov_b32 m0, s6
	v_readfirstlane_b32 s6, v70
	v_lshl_add_u64 v[4:5], v[50:51], 0, s[62:63]
	s_mov_b32 m0, s6
	v_or_b32_e32 v2, 0x380, v42
	v_readfirstlane_b32 s6, v71
	global_load_lds_dwordx4 v[4:5], off
	v_lshl_add_u64 v[4:5], v[2:3], 1, s[18:19]
	s_mov_b32 m0, s6
	v_readfirstlane_b32 s6, v72
	v_lshl_add_u64 v[4:5], v[52:53], 0, s[62:63]
	s_mov_b32 m0, s6
	v_or_b32_e32 v2, 0x380, v44
	v_readfirstlane_b32 s6, v73
	global_load_lds_dwordx4 v[4:5], off
	v_lshl_add_u64 v[4:5], v[2:3], 1, s[18:19]
	s_mov_b32 m0, s6
	s_nop 0
	s_and_saveexec_b64 s[6:7], s[4:5]
	s_cbranch_execz .LBB0_1553
	ds_read_b128 v[94:97], v87
	ds_read_b128 v[98:101], v87 offset:2048
	ds_read_b128 v[102:105], v86
	ds_read_b128 v[106:109], v86 offset:2048
	s_waitcnt lgkmcnt(0)
	v_mfma_f32_16x16x32_bf16 v[34:37], v[94:97], v[102:105], v[34:37]
	v_mfma_f32_16x16x32_bf16 v[30:33], v[98:101], v[102:105], v[30:33]
	v_mfma_f32_16x16x32_bf16 v[26:29], v[94:97], v[106:109], v[26:29]
	v_mfma_f32_16x16x32_bf16 v[22:25], v[98:101], v[106:109], v[22:25]
	ds_read_b128 v[102:105], v86 offset:4096
	ds_read_b128 v[106:109], v86 offset:6144
	s_waitcnt lgkmcnt(0)
	v_mfma_f32_16x16x32_bf16 v[18:21], v[94:97], v[102:105], v[18:21]
	v_mfma_f32_16x16x32_bf16 v[10:13], v[94:97], v[106:109], v[10:13]
	ds_read_b128 v[94:97], v89
	v_mfma_f32_16x16x32_bf16 v[14:17], v[98:101], v[102:105], v[14:17]
	v_mfma_f32_16x16x32_bf16 v[4:7], v[98:101], v[106:109], v[6:9]
	ds_read_b128 v[98:101], v89 offset:2048
	ds_read_b128 v[102:105], v88
	ds_read_b128 v[106:109], v88 offset:2048
	s_waitcnt lgkmcnt(0)
	v_mfma_f32_16x16x32_bf16 v[34:37], v[94:97], v[102:105], v[34:37]
	v_mfma_f32_16x16x32_bf16 v[30:33], v[98:101], v[102:105], v[30:33]
	v_mfma_f32_16x16x32_bf16 v[26:29], v[94:97], v[106:109], v[26:29]
	v_mfma_f32_16x16x32_bf16 v[22:25], v[98:101], v[106:109], v[22:25]
	ds_read_b128 v[102:105], v88 offset:4096
	ds_read_b128 v[106:109], v88 offset:6144
	s_waitcnt lgkmcnt(0)
	v_mfma_f32_16x16x32_bf16 v[18:21], v[94:97], v[102:105], v[18:21]
	v_mfma_f32_16x16x32_bf16 v[14:17], v[98:101], v[102:105], v[14:17]
	v_mfma_f32_16x16x32_bf16 v[10:13], v[94:97], v[106:109], v[10:13]
	v_mfma_f32_16x16x32_bf16 v[6:9], v[98:101], v[106:109], v[4:7]
.LBB0_1553:
	s_or_b64 exec, exec, s[6:7]
	v_readfirstlane_b32 s6, v74
	s_waitcnt vmcnt(0)
	s_barrier
	v_lshl_add_u64 v[4:5], v[46:47], 0, s[64:65]
	s_mov_b32 m0, s6
	v_or_b32_e32 v2, 0x3c0, v38
	v_readfirstlane_b32 s6, v75
	global_load_lds_dwordx4 v[4:5], off
	v_lshl_add_u64 v[4:5], v[2:3], 1, s[18:19]
	s_mov_b32 m0, s6
	v_readfirstlane_b32 s6, v76
	global_load_lds_dwordx4 v[4:5], off
	v_lshl_add_u64 v[4:5], v[48:49], 0, s[64:65]
	s_mov_b32 m0, s6
	v_or_b32_e32 v2, 0x3c0, v40
	v_readfirstlane_b32 s6, v77
	global_load_lds_dwordx4 v[4:5], off
	v_lshl_add_u64 v[4:5], v[2:3], 1, s[18:19]
	s_mov_b32 m0, s6
	v_readfirstlane_b32 s6, v78
	v_lshl_add_u64 v[4:5], v[50:51], 0, s[64:65]
	s_mov_b32 m0, s6
	v_or_b32_e32 v2, 0x3c0, v42
	v_readfirstlane_b32 s6, v79
	global_load_lds_dwordx4 v[4:5], off
	v_lshl_add_u64 v[4:5], v[2:3], 1, s[18:19]
	s_mov_b32 m0, s6
	v_readfirstlane_b32 s6, v80
	v_lshl_add_u64 v[4:5], v[52:53], 0, s[64:65]
	s_mov_b32 m0, s6
	v_or_b32_e32 v2, 0x3c0, v44
	v_readfirstlane_b32 s6, v81
	global_load_lds_dwordx4 v[4:5], off
	v_lshl_add_u64 v[4:5], v[2:3], 1, s[18:19]
	s_mov_b32 m0, s6
	s_nop 0
	s_and_saveexec_b64 s[6:7], s[4:5]
	s_cbranch_execz .LBB0_1555
	ds_read_b128 v[38:41], v83 offset:32768
	ds_read_b128 v[42:45], v83 offset:34816
	ds_read_b128 v[46:49], v82
	ds_read_b128 v[50:53], v82 offset:2048
	s_waitcnt lgkmcnt(0)
	v_mfma_f32_16x16x32_bf16 v[34:37], v[38:41], v[46:49], v[34:37]
	v_mfma_f32_16x16x32_bf16 v[30:33], v[42:45], v[46:49], v[30:33]
	v_mfma_f32_16x16x32_bf16 v[26:29], v[38:41], v[50:53], v[26:29]
	v_mfma_f32_16x16x32_bf16 v[22:25], v[42:45], v[50:53], v[22:25]
	ds_read_b128 v[46:49], v82 offset:4096
	ds_read_b128 v[50:53], v82 offset:6144
	s_waitcnt lgkmcnt(0)
	v_mfma_f32_16x16x32_bf16 v[18:21], v[38:41], v[46:49], v[18:21]
	v_mfma_f32_16x16x32_bf16 v[10:13], v[38:41], v[50:53], v[10:13]
	ds_read_b128 v[38:41], v85 offset:32768
	v_mfma_f32_16x16x32_bf16 v[14:17], v[42:45], v[46:49], v[14:17]
	v_mfma_f32_16x16x32_bf16 v[4:7], v[42:45], v[50:53], v[6:9]
	ds_read_b128 v[42:45], v85 offset:34816
	ds_read_b128 v[46:49], v84
	ds_read_b128 v[50:53], v84 offset:2048
	s_waitcnt lgkmcnt(0)
	v_mfma_f32_16x16x32_bf16 v[34:37], v[38:41], v[46:49], v[34:37]
	v_mfma_f32_16x16x32_bf16 v[30:33], v[42:45], v[46:49], v[30:33]
	v_mfma_f32_16x16x32_bf16 v[26:29], v[38:41], v[50:53], v[26:29]
	v_mfma_f32_16x16x32_bf16 v[22:25], v[42:45], v[50:53], v[22:25]
	ds_read_b128 v[46:49], v84 offset:4096
	ds_read_b128 v[50:53], v84 offset:6144
	s_waitcnt lgkmcnt(0)
	v_mfma_f32_16x16x32_bf16 v[18:21], v[38:41], v[46:49], v[18:21]
	v_mfma_f32_16x16x32_bf16 v[14:17], v[42:45], v[46:49], v[14:17]
	v_mfma_f32_16x16x32_bf16 v[10:13], v[38:41], v[50:53], v[10:13]
	v_mfma_f32_16x16x32_bf16 v[6:9], v[42:45], v[50:53], v[4:7]
